# MLA loop: K/V/k_pe global loads issued two tiles ahead (two register sets, loop unrolled by two) to hide memory latency
# speedup vs baseline: 1.0014x; 1.0014x over previous
.LBB0_496:
	s_add_i32 s19, s15, 2
	s_cmp_lt_u32 s19, s5
	s_cselect_b32 s10, 0, s5
	s_cselect_b32 s11, s59, s14
	s_lshl_b32 s10, s10, 6
	s_sub_i32 s18, s11, s10
	s_and_saveexec_b64 s[10:11], s[38:39]
	s_cbranch_execz .Lmla2_ent_noe
	v_add_u32_e32 v236, s18, v124
	v_ashrrev_i32_e32 v237, 31, v236
	v_lshlrev_b64 v[236:237], 6, v[236:237]
	v_lshl_add_u64 v[236:237], v[116:117], 0, v[236:237]
	global_load_dwordx4 v[94:97], v[236:237], off
.Lmla2_ent_noe:
	s_or_b64 exec, exec, s[10:11]
	v_add_u32_e32 v236, s18, v125
	v_ashrrev_i32_e32 v237, 31, v236
	v_lshlrev_b64 v[236:237], 10, v[236:237]
	v_lshl_add_u64 v[236:237], v[114:115], 0, v[236:237]
	global_load_dwordx4 v[106:109], v[236:237], off
	global_load_dwordx4 v[102:105], v[236:237], off offset:128
.Lmla2_odd:
	s_add_i32 s17, s15, 2
	s_add_i32 s15, s15, 1
	s_bitcmp1_b32 s15, 0
	s_cselect_b32 s18, 0x6400, 0
	v_add_u32_e32 v126, s18, v123
	v_add_u32_e32 v234, s18, v118
	ds_read_b128 v[148:151], v126
	ds_read_b128 v[152:155], v126 offset:6656
	ds_read_b128 v[156:159], v126 offset:32
	ds_read_b128 v[160:163], v126 offset:6688
	ds_read_b128 v[164:167], v126 offset:64
	ds_read_b128 v[168:171], v126 offset:6720
	ds_read_b128 v[172:175], v126 offset:96
	ds_read_b128 v[176:179], v126 offset:6752
	ds_read_b128 v[180:183], v126 offset:128
	ds_read_b128 v[184:187], v126 offset:6784
	ds_read_b128 v[188:191], v126 offset:160
	ds_read_b128 v[192:195], v126 offset:6816
	v_mov_b64_e32 v[50:51], v[98:99]
	v_mov_b64_e32 v[52:53], v[100:101]
	v_mfma_f32_32x32x16_bf16 v[34:49], v[90:93], v[98:101], 0
	s_cmp_lt_u32 s15, s16
	s_cbranch_scc0 .Lmla2_odd_nold
	s_add_i32 s19, s15, 2
	s_cmp_lt_u32 s19, s5
	s_cselect_b32 s10, 0, s5
	s_cselect_b32 s11, s59, s14
	s_lshl_b32 s10, s10, 6
	s_sub_i32 s18, s11, s10
	s_add_i32 s18, s18, 64
	s_and_saveexec_b64 s[10:11], s[38:39]
	s_cbranch_execz .Lmla2_odd_noe
	v_add_u32_e32 v236, s18, v124
	v_ashrrev_i32_e32 v237, 31, v236
	v_lshlrev_b64 v[236:237], 6, v[236:237]
	v_lshl_add_u64 v[236:237], v[116:117], 0, v[236:237]
	global_load_dwordx4 v[226:229], v[236:237], off
.Lmla2_odd_noe:
	s_or_b64 exec, exec, s[10:11]
	v_add_u32_e32 v236, s18, v125
	v_ashrrev_i32_e32 v237, 31, v236
	v_lshlrev_b64 v[236:237], 10, v[236:237]
	v_lshl_add_u64 v[236:237], v[114:115], 0, v[236:237]
	global_load_dwordx4 v[218:221], v[236:237], off
	global_load_dwordx4 v[222:225], v[236:237], off offset:128
.Lmla2_odd_nold:
	s_nop 0
	v_mfma_f32_32x32x16_bf16 v[50:65], v[90:93], v[50:53], 0
	s_waitcnt lgkmcnt(11)
	v_mfma_f32_32x32x16_bf16 v[34:49], v[148:151], v[74:77], v[34:49]
	s_waitcnt lgkmcnt(10)
	v_mfma_f32_32x32x16_bf16 v[50:65], v[152:155], v[74:77], v[50:65]
	s_waitcnt lgkmcnt(9)
	v_mfma_f32_32x32x16_bf16 v[34:49], v[156:159], v[66:69], v[34:49]
	s_waitcnt lgkmcnt(8)
	v_mfma_f32_32x32x16_bf16 v[50:65], v[160:163], v[66:69], v[50:65]
	s_waitcnt lgkmcnt(7)
	v_mfma_f32_32x32x16_bf16 v[34:49], v[164:167], v[82:85], v[34:49]
	s_waitcnt lgkmcnt(6)
	v_mfma_f32_32x32x16_bf16 v[50:65], v[168:171], v[82:85], v[50:65]
	s_waitcnt lgkmcnt(5)
	v_mfma_f32_32x32x16_bf16 v[34:49], v[172:175], v[70:73], v[34:49]
	s_waitcnt lgkmcnt(4)
	v_mfma_f32_32x32x16_bf16 v[50:65], v[176:179], v[70:73], v[50:65]
	s_waitcnt lgkmcnt(3)
	v_mfma_f32_32x32x16_bf16 v[34:49], v[180:183], v[86:89], v[34:49]
	s_waitcnt lgkmcnt(2)
	v_mfma_f32_32x32x16_bf16 v[50:65], v[184:187], v[86:89], v[50:65]
	s_waitcnt lgkmcnt(1)
	v_mfma_f32_32x32x16_bf16 v[34:49], v[188:191], v[78:81], v[34:49]
	s_waitcnt lgkmcnt(0)
	v_mfma_f32_32x32x16_bf16 v[50:65], v[192:195], v[78:81], v[50:65]
	ds_read_b64_tr_b16 v[196:197], v234 offset:13312
	ds_read_b64_tr_b16 v[198:199], v234 offset:14848
	ds_read_b64_tr_b16 v[200:201], v234 offset:16384
	ds_read_b64_tr_b16 v[202:203], v234 offset:17920
	ds_read_b64_tr_b16 v[204:205], v234 offset:19456
	ds_read_b64_tr_b16 v[206:207], v234 offset:20992
	ds_read_b64_tr_b16 v[214:215], v234 offset:22528
	ds_read_b64_tr_b16 v[216:217], v234 offset:24064
	s_nop 4
	v_max_f32_e32 v126, v35, v35
	v_max_f32_e32 v132, v34, v34
	v_max_f32_e32 v126, v132, v126
	v_max3_f32 v128, v36, v37, v51
	v_max3_f32 v126, v126, v50, v52
	v_max3_f32 v126, v126, v53, v38
	v_max3_f32 v128, v128, v40, v41
	v_max3_f32 v126, v126, v39, v54
	v_max3_f32 v128, v128, v56, v57
	v_max3_f32 v126, v126, v55, v42
	v_max3_f32 v128, v128, v44, v45
	v_max3_f32 v126, v126, v43, v58
	v_max3_f32 v128, v128, v60, v61
	v_max3_f32 v126, v126, v59, v46
	v_max3_f32 v128, v128, v48, v49
	v_max3_f32 v126, v126, v47, v62
	v_max3_f32 v128, v128, v64, v65
	v_max3_f32 v126, v126, v63, v128
	ds_bpermute_b32 v128, v113, v126
	s_waitcnt lgkmcnt(0)
	ds_read_b64_tr_b16 v[148:149], v234 offset:13376
	ds_read_b64_tr_b16 v[150:151], v234 offset:14912
	ds_read_b64_tr_b16 v[152:153], v234 offset:16448
	ds_read_b64_tr_b16 v[154:155], v234 offset:17984
	ds_read_b64_tr_b16 v[156:157], v234 offset:19520
	ds_read_b64_tr_b16 v[158:159], v234 offset:21056
	ds_read_b64_tr_b16 v[160:161], v234 offset:22592
	ds_read_b64_tr_b16 v[162:163], v234 offset:24128
	v_max_f32_e32 v128, v128, v128
	v_max_f32_e32 v126, v126, v128
	v_cmp_lt_f32_e32 vcc, s7, v126
	s_cbranch_vccz .Lmla2_odd_nors
	v_max_f32_e32 v126, v126, v126
	v_max_f32_e32 v126, 0, v126
	v_add_f32_e32 v126, v127, v126
	v_cvt_pk_bf16_f32 v126, v126, v1
	s_nop 0
	v_lshlrev_b32_e32 v126, 16, v126
	s_and_saveexec_b64 s[10:11], s[36:37]
	s_cbranch_execz .Lmla2_odd_rs1
	v_xor_b32_e32 v128, 0x80000000, v126
	v_cvt_pk_bf16_f32 v128, v128, v1
	s_nop 0
	v_bfi_b32 v98, s2, v128, v98

.Lmla2_odd_ep:
	v_exp_f32_e32 v34, v34
	v_exp_f32_e32 v35, v35
	v_exp_f32_e32 v36, v36
	v_exp_f32_e32 v37, v37
	v_exp_f32_e32 v38, v38
	v_exp_f32_e32 v39, v39
	v_exp_f32_e32 v40, v40
	v_exp_f32_e32 v41, v41
	v_cvt_pk_bf16_f32 v128, v34, v35
	v_cvt_pk_bf16_f32 v129, v36, v37
	v_cvt_pk_bf16_f32 v130, v38, v39
	v_cvt_pk_bf16_f32 v131, v40, v41
	v_exp_f32_e32 v42, v42
	v_exp_f32_e32 v43, v43
	v_mfma_f32_32x32x16_bf16 v[2:17], v[196:199], v[128:131], v[2:17]
	s_waitcnt lgkmcnt(6)
	v_mfma_f32_32x32x16_bf16 v[18:33], v[148:151], v[128:131], v[18:33]
	v_exp_f32_e32 v44, v44
	v_exp_f32_e32 v45, v45
	v_exp_f32_e32 v46, v46
	v_exp_f32_e32 v47, v47
	v_exp_f32_e32 v48, v48
	v_exp_f32_e32 v49, v49
	v_cvt_pk_bf16_f32 v136, v42, v43
	v_cvt_pk_bf16_f32 v137, v44, v45
	v_cvt_pk_bf16_f32 v138, v46, v47
	v_cvt_pk_bf16_f32 v139, v48, v49
	v_exp_f32_e32 v50, v50
	v_exp_f32_e32 v51, v51
	v_mfma_f32_32x32x16_bf16 v[2:17], v[200:203], v[136:139], v[2:17]
	s_waitcnt lgkmcnt(4)
	v_mfma_f32_32x32x16_bf16 v[18:33], v[152:155], v[136:139], v[18:33]
	v_exp_f32_e32 v52, v52
	v_exp_f32_e32 v53, v53
	v_exp_f32_e32 v54, v54
	v_exp_f32_e32 v55, v55
	v_exp_f32_e32 v56, v56
	v_exp_f32_e32 v57, v57
	v_cvt_pk_bf16_f32 v132, v50, v51
	v_cvt_pk_bf16_f32 v133, v52, v53
	v_cvt_pk_bf16_f32 v134, v54, v55
	v_cvt_pk_bf16_f32 v135, v56, v57
	v_exp_f32_e32 v58, v58
	v_exp_f32_e32 v59, v59
	v_mfma_f32_32x32x16_bf16 v[2:17], v[204:207], v[132:135], v[2:17]
	s_waitcnt lgkmcnt(2)
	v_mfma_f32_32x32x16_bf16 v[18:33], v[156:159], v[132:135], v[18:33]
	v_exp_f32_e32 v60, v60
	v_exp_f32_e32 v61, v61
	v_exp_f32_e32 v62, v62
	v_exp_f32_e32 v63, v63
	v_exp_f32_e32 v64, v64
	v_exp_f32_e32 v65, v65
	v_cvt_pk_bf16_f32 v140, v58, v59
	v_cvt_pk_bf16_f32 v141, v60, v61
	v_cvt_pk_bf16_f32 v142, v62, v63
	v_cvt_pk_bf16_f32 v143, v64, v65
	s_bitcmp1_b32 s17, 0
	s_cselect_b32 s10, 0x6400, 0
	s_add_i32 s17, s10, 0
	v_mfma_f32_32x32x16_bf16 v[2:17], v[214:217], v[140:143], v[2:17]
	s_waitcnt lgkmcnt(0)
	v_mfma_f32_32x32x16_bf16 v[18:33], v[160:163], v[140:143], v[18:33]
	v_add_u32_e32 v238, s17, v120
	v_add_u32_e32 v239, s17, v121
	v_add3_u32 v235, s17, v112, v122
	s_cmp_lt_u32 s15, s16
	s_cbranch_scc0 .Lmla2_odd_w0
	s_waitcnt vmcnt(2)
	s_branch .Lmla2_odd_w1

.Lmla2_odd_w1:
	ds_write_b128 v238, v[106:109]
	ds_write_b128 v239, v[102:105] offset:13312
	s_and_saveexec_b64 s[10:11], s[38:39]
	ds_write_b128 v235, v[94:97] offset:128
	s_or_b64 exec, exec, s[10:11]
	v_add_f32_e32 v34, v50, v34
	v_add_f32_e32 v35, v51, v35
	v_add_f32_e32 v34, 0, v34
	v_add_f32_e32 v36, v52, v36
	v_add_f32_e32 v34, v35, v34
	v_add_f32_e32 v37, v53, v37
	v_add_f32_e32 v34, v36, v34
	v_add_f32_e32 v38, v54, v38
	v_add_f32_e32 v34, v37, v34
	v_add_f32_e32 v39, v55, v39
	v_add_f32_e32 v34, v38, v34
	v_add_f32_e32 v40, v56, v40
	v_add_f32_e32 v34, v39, v34
	v_add_f32_e32 v41, v57, v41
	v_add_f32_e32 v34, v40, v34
	v_add_f32_e32 v42, v58, v42
	v_add_f32_e32 v34, v41, v34
	v_add_f32_e32 v43, v59, v43
	v_add_f32_e32 v34, v42, v34
	v_add_f32_e32 v44, v60, v44
	v_add_f32_e32 v34, v43, v34
	v_add_f32_e32 v45, v61, v45
	v_add_f32_e32 v34, v44, v34
	v_add_f32_e32 v46, v62, v46
	v_add_f32_e32 v34, v45, v34
	v_add_f32_e32 v47, v63, v47
	v_add_f32_e32 v34, v46, v34
	v_add_f32_e32 v48, v64, v48
	v_add_f32_e32 v34, v47, v34
	v_add_f32_e32 v49, v65, v49
	v_add_f32_e32 v34, v48, v34
	v_add_f32_e32 v34, v49, v34
	v_add_f32_e32 v119, v119, v34
	v_add_u32_e32 v124, 64, v124
	s_cmp_lg_u32 s16, s15
	v_add_u32_e32 v125, 64, v125
	s_waitcnt lgkmcnt(0)
	s_barrier
	s_cbranch_scc0 .LBB0_507
	v_mov_b32_e32 v127, v126
.Lmla2_even:
	s_add_i32 s17, s15, 2
	s_add_i32 s15, s15, 1
	s_bitcmp1_b32 s15, 0
	s_cselect_b32 s18, 0x6400, 0
	v_add_u32_e32 v126, s18, v123
	v_add_u32_e32 v234, s18, v118
	ds_read_b128 v[148:151], v126
	ds_read_b128 v[152:155], v126 offset:6656
	ds_read_b128 v[156:159], v126 offset:32
	ds_read_b128 v[160:163], v126 offset:6688
	ds_read_b128 v[164:167], v126 offset:64
	ds_read_b128 v[168:171], v126 offset:6720
	ds_read_b128 v[172:175], v126 offset:96
	ds_read_b128 v[176:179], v126 offset:6752
	ds_read_b128 v[180:183], v126 offset:128
	ds_read_b128 v[184:187], v126 offset:6784
	ds_read_b128 v[188:191], v126 offset:160
	ds_read_b128 v[192:195], v126 offset:6816
	v_mov_b64_e32 v[50:51], v[98:99]
	v_mov_b64_e32 v[52:53], v[100:101]
	v_mfma_f32_32x32x16_bf16 v[34:49], v[90:93], v[98:101], 0
	s_cmp_lt_u32 s15, s16
	s_cbranch_scc0 .Lmla2_even_nold
	s_add_i32 s19, s15, 2
	s_cmp_lt_u32 s19, s5
	s_cselect_b32 s10, 0, s5
	s_cselect_b32 s11, s59, s14
	s_lshl_b32 s10, s10, 6
	s_sub_i32 s18, s11, s10
	s_add_i32 s18, s18, 64
	s_and_saveexec_b64 s[10:11], s[38:39]
	s_cbranch_execz .Lmla2_even_noe
	v_add_u32_e32 v236, s18, v124
	v_ashrrev_i32_e32 v237, 31, v236
	v_lshlrev_b64 v[236:237], 6, v[236:237]
	v_lshl_add_u64 v[236:237], v[116:117], 0, v[236:237]
	global_load_dwordx4 v[94:97], v[236:237], off

.Lmla2_even_w1:
	ds_write_b128 v238, v[218:221]
	ds_write_b128 v239, v[222:225] offset:13312
	s_and_saveexec_b64 s[10:11], s[38:39]
	ds_write_b128 v235, v[226:229] offset:128
	s_or_b64 exec, exec, s[10:11]
	v_add_f32_e32 v34, v50, v34
	v_add_f32_e32 v35, v51, v35
	v_add_f32_e32 v34, 0, v34
	v_add_f32_e32 v36, v52, v36
	v_add_f32_e32 v34, v35, v34
	v_add_f32_e32 v37, v53, v37
	v_add_f32_e32 v34, v36, v34
	v_add_f32_e32 v38, v54, v38
	v_add_f32_e32 v34, v37, v34
	v_add_f32_e32 v39, v55, v39
	v_add_f32_e32 v34, v38, v34
	v_add_f32_e32 v40, v56, v40
	v_add_f32_e32 v34, v39, v34
	v_add_f32_e32 v41, v57, v41
	v_add_f32_e32 v34, v40, v34
	v_add_f32_e32 v42, v58, v42
	v_add_f32_e32 v34, v41, v34
	v_add_f32_e32 v43, v59, v43
	v_add_f32_e32 v34, v42, v34
	v_add_f32_e32 v44, v60, v44
	v_add_f32_e32 v34, v43, v34
	v_add_f32_e32 v45, v61, v45
	v_add_f32_e32 v34, v44, v34
	v_add_f32_e32 v46, v62, v46
	v_add_f32_e32 v34, v45, v34
	v_add_f32_e32 v47, v63, v47
	v_add_f32_e32 v34, v46, v34
	v_add_f32_e32 v48, v64, v48
	v_add_f32_e32 v34, v47, v34
	v_add_f32_e32 v49, v65, v49
	v_add_f32_e32 v34, v48, v34
	v_add_f32_e32 v34, v49, v34
	v_add_f32_e32 v119, v119, v34
	v_add_u32_e32 v124, 64, v124
	s_cmp_lg_u32 s16, s15
	v_add_u32_e32 v125, 64, v125
	s_waitcnt lgkmcnt(0)
	s_barrier
	s_cbranch_scc0 .LBB0_507
	v_mov_b32_e32 v127, v126
	s_branch .Lmla2_odd
